# v5 plus .p2align 6 on the ten GEMM K-loop heads (code placement pin)
# baseline (speedup 1.0000x reference)
;     __device__ __forceinline__ const char* pa(const Gemm& g, const Unit& u, size_t tstep) const { return (const char*)g.A + (size_t)u.pm * tstep; }
;     __device__ __forceinline__ const char* pb(const Gemm& g, const Unit& u, size_t tstep) const { return (const char*)g.Bt + (size_t)u.pn * tstep; }
;     __device__ __forceinline__ const char* pa(const Gemm& g, const Unit& u, size_t tstep) const { return (const char*)g.A + (size_t)(u.pn >> 1) * 512 + (size_t)u.pm * tstep; }
;     __device__ __forceinline__ bool next(int i, Unit& u) const { const int ti = i / 3, sg = i - 3 * ti; if (!StaticOrder::next(ti, u)) return false; u.seg = sg; return true; }
;     __device__ __forceinline__ const char* pa(const Gemm& g, const Unit& u, size_t tstep) const { return (const char*)g.A + (size_t)u.seg * astride + (size_t)u.pm * tstep; }
;     __device__ __forceinline__ const char* pb(const Gemm& g, const Unit& u, size_t tstep) const { return (const char*)g.Bt + (size_t)u.seg * bstride + (size_t)u.pn * tstep; }
;     ...
;     for (int a = 0; a < 2; ++a)
; #pragma unroll
;         for (int b = 0; b < 2; ++b)
; #pragma unroll
;             for (int m = 0; m < 4; ++m)
; #pragma unroll
;                 for (int n = 0; n < 2; ++n) acc[a][b][m][n] = (f32x4){0.f, 0.f, 0.f, 0.f};
;     ...
;     for (;;) {
;         const bool has_next = S.next(ui + 1, nxt);
;         const char* nA = has_next ? S.pa(g, nxt, tstepA) : cA; const char* nB = has_next ? S.pb(g, nxt, tstepB) : cB;
;         for (int t = 0; t < nt; t += 2) {
;             const bool last = (t == nt - 2);
;             const char* a1 = cA + (size_t)(t + 1) * kstep;
;             const char* a2 = last ? nA : cA + (size_t)(t + 2) * kstep; const char* b2 = last ? nB : cB + (size_t)(t + 2) * kstep;
;             const char* a3 = a2 + kstep; const char* b3 = b2 + kstep;
.LBB0_537:
	s_ashr_i32 s57, s56, 31
	s_lshl_b64 s[34:35], s[56:57], 19
	s_add_u32 s58, s11, s34
	s_addc_u32 s59, s24, s35
	s_and_b64 s[34:35], s[42:43], exec
	s_cselect_b32 s6, s59, s65
	s_cselect_b32 s15, s58, s64
	s_ashr_i32 s55, s54, 31
	s_lshl_b64 s[34:35], s[54:55], 19
	s_add_u32 s60, s79, s34
	s_addc_u32 s61, s80, s35
	s_and_b64 s[34:35], s[42:43], exec
	s_cselect_b32 s34, s61, s67
	s_cselect_b32 s35, s60, s66
	s_add_u32 s64, s64, 0x40080
	s_addc_u32 s65, s65, 0
	s_add_u32 s45, s66, 0x100
	v_mov_b32_e32 v2, 0
	s_addc_u32 s55, s67, 0
	s_mov_b32 s57, -2
	s_waitcnt lgkmcnt(0)
	v_mov_b32_e32 v3, v2
	v_mov_b64_e32 v[4:5], 0
	v_mov_b64_e32 v[6:7], 0
	v_mov_b64_e32 v[8:9], 0
	v_mov_b64_e32 v[10:11], 0
	v_mov_b64_e32 v[12:13], 0
	v_mov_b64_e32 v[14:15], 0
	v_mov_b64_e32 v[16:17], 0
	v_mov_b64_e32 v[18:19], 0
	v_mov_b64_e32 v[20:21], 0
	v_mov_b64_e32 v[22:23], 0
	v_mov_b64_e32 v[24:25], 0
	v_mov_b64_e32 v[26:27], 0
	v_mov_b64_e32 v[28:29], 0
	v_mov_b64_e32 v[30:31], 0
	v_mov_b64_e32 v[32:33], 0
	v_mov_b64_e32 v[36:37], 0
	v_mov_b64_e32 v[38:39], 0
	v_mov_b64_e32 v[40:41], 0
	v_mov_b64_e32 v[42:43], 0
	v_mov_b64_e32 v[44:45], 0
	v_mov_b64_e32 v[46:47], 0
	v_mov_b64_e32 v[48:49], 0
	v_mov_b64_e32 v[50:51], 0
	v_mov_b64_e32 v[52:53], 0
	v_mov_b64_e32 v[54:55], 0
	v_mov_b64_e32 v[56:57], 0
	v_mov_b64_e32 v[58:59], 0
	v_mov_b64_e32 v[60:61], 0
	v_mov_b64_e32 v[62:63], 0
	v_mov_b64_e32 v[64:65], 0
	v_mov_b64_e32 v[66:67], 0
	v_mov_b64_e32 v[68:69], 0
	v_mov_b64_e32 v[70:71], 0
	v_mov_b64_e32 v[72:73], 0
	v_mov_b64_e32 v[74:75], 0
	v_mov_b64_e32 v[76:77], 0
	v_mov_b64_e32 v[78:79], 0
	v_mov_b64_e32 v[80:81], 0
	v_mov_b64_e32 v[82:83], 0
	v_mov_b64_e32 v[84:85], 0
	v_mov_b64_e32 v[86:87], 0
	v_mov_b64_e32 v[88:89], 0
	v_mov_b64_e32 v[90:91], 0
	v_mov_b64_e32 v[92:93], 0
	v_mov_b64_e32 v[94:95], 0
	v_mov_b64_e32 v[96:97], 0
	v_mov_b64_e32 v[98:99], 0
	v_mov_b64_e32 v[100:101], 0
	v_mov_b64_e32 v[102:103], 0
	v_mov_b64_e32 v[104:105], 0
	v_mov_b64_e32 v[106:107], 0
	v_mov_b64_e32 v[108:109], 0
	v_mov_b64_e32 v[110:111], 0
	v_mov_b64_e32 v[112:113], 0
	v_mov_b64_e32 v[114:115], 0
	v_mov_b64_e32 v[116:117], 0
	v_mov_b64_e32 v[118:119], 0
	v_mov_b64_e32 v[120:121], 0
	v_mov_b64_e32 v[122:123], 0
	v_mov_b64_e32 v[124:125], 0
	v_mov_b64_e32 v[126:127], 0
	v_mov_b64_e32 v[128:129], 0
	v_mov_b64_e32 v[130:131], 0
	.p2align	6

;     __device__ __forceinline__ const char* pa(const Gemm& g, const Unit& u, size_t tstep) const { return (const char*)g.A + (size_t)u.pm * tstep; }
;     __device__ __forceinline__ const char* pb(const Gemm& g, const Unit& u, size_t tstep) const { return (const char*)g.Bt + (size_t)u.pn * tstep; }
;     __device__ __forceinline__ const char* pa(const Gemm& g, const Unit& u, size_t tstep) const { return (const char*)g.A + (size_t)(u.pn >> 1) * 512 + (size_t)u.pm * tstep; }
;     __device__ __forceinline__ bool next(int i, Unit& u) const { const int ti = i / 3, sg = i - 3 * ti; if (!StaticOrder::next(ti, u)) return false; u.seg = sg; return true; }
;     __device__ __forceinline__ const char* pa(const Gemm& g, const Unit& u, size_t tstep) const { return (const char*)g.A + (size_t)u.seg * astride + (size_t)u.pm * tstep; }
;     __device__ __forceinline__ const char* pb(const Gemm& g, const Unit& u, size_t tstep) const { return (const char*)g.Bt + (size_t)u.seg * bstride + (size_t)u.pn * tstep; }
;     ...
;     for (int a = 0; a < 2; ++a)
; #pragma unroll
;         for (int b = 0; b < 2; ++b)
; #pragma unroll
;             for (int m = 0; m < 4; ++m)
; #pragma unroll
;                 for (int n = 0; n < 2; ++n) acc[a][b][m][n] = (f32x4){0.f, 0.f, 0.f, 0.f};
;     ...
;     for (;;) {
;         const bool has_next = S.next(ui + 1, nxt);
;         const char* nA = has_next ? S.pa(g, nxt, tstepA) : cA; const char* nB = has_next ? S.pb(g, nxt, tstepB) : cB;
;         for (int t = 0; t < nt; t += 2) {
;             const bool last = (t == nt - 2);
;             const char* a1 = cA + (size_t)(t + 1) * kstep;
;             const char* a2 = last ? nA : cA + (size_t)(t + 2) * kstep; const char* b2 = last ? nB : cB + (size_t)(t + 2) * kstep;
;             const char* a3 = a2 + kstep; const char* b3 = b2 + kstep;
.LBB0_607:
	s_ashr_i32 s37, s36, 31
	s_lshl_b64 s[40:41], s[36:37], 20
	s_add_u32 s40, s8, s40
	s_addc_u32 s41, s10, s41
	s_and_b64 s[42:43], s[38:39], exec
	s_cselect_b32 s37, s41, s51
	s_cselect_b32 s58, s40, s50
	s_ashr_i32 s31, s30, 31
	s_lshl_b64 s[42:43], s[30:31], 20
	s_add_u32 s42, s9, s42
	s_addc_u32 s43, s76, s43
	s_and_b64 s[54:55], s[38:39], exec
	s_cselect_b32 s31, s43, s53
	s_cselect_b32 s59, s42, s52
	s_add_u32 s50, s50, 0x80080
	s_addc_u32 s51, s51, 0
	s_add_u32 s60, s52, 0x100
	v_mov_b32_e32 v2, 0
	s_addc_u32 s61, s53, 0
	s_mov_b32 s62, -2
	v_mov_b32_e32 v3, v2
	v_mov_b64_e32 v[4:5], 0
	v_mov_b64_e32 v[6:7], 0
	v_mov_b64_e32 v[8:9], 0
	v_mov_b64_e32 v[10:11], 0
	v_mov_b64_e32 v[12:13], 0
	v_mov_b64_e32 v[14:15], 0
	v_mov_b64_e32 v[16:17], 0
	v_mov_b64_e32 v[18:19], 0
	v_mov_b64_e32 v[20:21], 0
	v_mov_b64_e32 v[22:23], 0
	v_mov_b64_e32 v[24:25], 0
	v_mov_b64_e32 v[26:27], 0
	v_mov_b64_e32 v[28:29], 0
	v_mov_b64_e32 v[30:31], 0
	v_mov_b64_e32 v[32:33], 0
	v_mov_b64_e32 v[36:37], 0
	v_mov_b64_e32 v[38:39], 0
	v_mov_b64_e32 v[40:41], 0
	v_mov_b64_e32 v[42:43], 0
	v_mov_b64_e32 v[44:45], 0
	v_mov_b64_e32 v[46:47], 0
	v_mov_b64_e32 v[48:49], 0
	v_mov_b64_e32 v[50:51], 0
	v_mov_b64_e32 v[52:53], 0
	v_mov_b64_e32 v[54:55], 0
	v_mov_b64_e32 v[56:57], 0
	v_mov_b64_e32 v[58:59], 0
	v_mov_b64_e32 v[60:61], 0
	v_mov_b64_e32 v[62:63], 0
	v_mov_b64_e32 v[64:65], 0
	v_mov_b64_e32 v[66:67], 0
	v_mov_b64_e32 v[68:69], 0
	v_mov_b64_e32 v[70:71], 0
	v_mov_b64_e32 v[72:73], 0
	v_mov_b64_e32 v[74:75], 0
	v_mov_b64_e32 v[76:77], 0
	v_mov_b64_e32 v[78:79], 0
	v_mov_b64_e32 v[80:81], 0
	v_mov_b64_e32 v[82:83], 0
	v_mov_b64_e32 v[84:85], 0
	v_mov_b64_e32 v[86:87], 0
	v_mov_b64_e32 v[88:89], 0
	v_mov_b64_e32 v[90:91], 0
	v_mov_b64_e32 v[92:93], 0
	v_mov_b64_e32 v[94:95], 0
	v_mov_b64_e32 v[96:97], 0
	v_mov_b64_e32 v[98:99], 0
	v_mov_b64_e32 v[100:101], 0
	v_mov_b64_e32 v[102:103], 0
	v_mov_b64_e32 v[104:105], 0
	v_mov_b64_e32 v[106:107], 0
	v_mov_b64_e32 v[108:109], 0
	v_mov_b64_e32 v[110:111], 0
	v_mov_b64_e32 v[112:113], 0
	v_mov_b64_e32 v[114:115], 0
	v_mov_b64_e32 v[116:117], 0
	v_mov_b64_e32 v[118:119], 0
	v_mov_b64_e32 v[120:121], 0
	v_mov_b64_e32 v[122:123], 0
	v_mov_b64_e32 v[124:125], 0
	v_mov_b64_e32 v[126:127], 0
	v_mov_b64_e32 v[128:129], 0
	v_mov_b64_e32 v[130:131], 0
	.p2align	6

;     __device__ __forceinline__ const char* pa(const Gemm& g, const Unit& u, size_t tstep) const { return (const char*)g.A + (size_t)u.pm * tstep; }
;     __device__ __forceinline__ const char* pb(const Gemm& g, const Unit& u, size_t tstep) const { return (const char*)g.Bt + (size_t)u.pn * tstep; }
;     __device__ __forceinline__ const char* pa(const Gemm& g, const Unit& u, size_t tstep) const { return (const char*)g.A + (size_t)(u.pn >> 1) * 512 + (size_t)u.pm * tstep; }
;     __device__ __forceinline__ bool next(int i, Unit& u) const { const int ti = i / 3, sg = i - 3 * ti; if (!StaticOrder::next(ti, u)) return false; u.seg = sg; return true; }
;     __device__ __forceinline__ const char* pa(const Gemm& g, const Unit& u, size_t tstep) const { return (const char*)g.A + (size_t)u.seg * astride + (size_t)u.pm * tstep; }
;     __device__ __forceinline__ const char* pb(const Gemm& g, const Unit& u, size_t tstep) const { return (const char*)g.Bt + (size_t)u.seg * bstride + (size_t)u.pn * tstep; }
;     ...
;     for (int a = 0; a < 2; ++a)
; #pragma unroll
;         for (int b = 0; b < 2; ++b)
; #pragma unroll
;             for (int m = 0; m < 4; ++m)
; #pragma unroll
;                 for (int n = 0; n < 2; ++n) acc[a][b][m][n] = (f32x4){0.f, 0.f, 0.f, 0.f};
;     ...
;     for (;;) {
;         const bool has_next = S.next(ui + 1, nxt);
;         const char* nA = has_next ? S.pa(g, nxt, tstepA) : cA; const char* nB = has_next ? S.pb(g, nxt, tstepB) : cB;
;         for (int t = 0; t < nt; t += 2) {
;             const bool last = (t == nt - 2);
;             const char* a1 = cA + (size_t)(t + 1) * kstep;
;             const char* a2 = last ? nA : cA + (size_t)(t + 2) * kstep; const char* b2 = last ? nB : cB + (size_t)(t + 2) * kstep;
;             const char* a3 = a2 + kstep; const char* b3 = b2 + kstep;
.LBB0_693:
	s_add_u32 s64, s44, 0x100
	v_mov_b32_e32 v2, 0
	s_addc_u32 s65, s45, 0
	s_mov_b32 s66, -2
	v_mov_b32_e32 v3, v2
	v_mov_b64_e32 v[4:5], 0
	v_mov_b64_e32 v[6:7], 0
	v_mov_b64_e32 v[8:9], 0
	v_mov_b64_e32 v[10:11], 0
	v_mov_b64_e32 v[12:13], 0
	v_mov_b64_e32 v[14:15], 0
	v_mov_b64_e32 v[16:17], 0
	v_mov_b64_e32 v[18:19], 0
	v_mov_b64_e32 v[20:21], 0
	v_mov_b64_e32 v[22:23], 0
	v_mov_b64_e32 v[24:25], 0
	v_mov_b64_e32 v[26:27], 0
	v_mov_b64_e32 v[28:29], 0
	v_mov_b64_e32 v[30:31], 0
	v_mov_b64_e32 v[32:33], 0
	v_mov_b64_e32 v[36:37], 0
	v_mov_b64_e32 v[38:39], 0
	v_mov_b64_e32 v[40:41], 0
	v_mov_b64_e32 v[42:43], 0
	v_mov_b64_e32 v[44:45], 0
	v_mov_b64_e32 v[46:47], 0
	v_mov_b64_e32 v[48:49], 0
	v_mov_b64_e32 v[50:51], 0
	v_mov_b64_e32 v[52:53], 0
	v_mov_b64_e32 v[54:55], 0
	v_mov_b64_e32 v[56:57], 0
	v_mov_b64_e32 v[58:59], 0
	v_mov_b64_e32 v[60:61], 0
	v_mov_b64_e32 v[62:63], 0
	v_mov_b64_e32 v[64:65], 0
	v_mov_b64_e32 v[66:67], 0
	v_mov_b64_e32 v[68:69], 0
	v_mov_b64_e32 v[70:71], 0
	v_mov_b64_e32 v[72:73], 0
	v_mov_b64_e32 v[74:75], 0
	v_mov_b64_e32 v[76:77], 0
	v_mov_b64_e32 v[78:79], 0
	v_mov_b64_e32 v[80:81], 0
	v_mov_b64_e32 v[82:83], 0
	v_mov_b64_e32 v[84:85], 0
	v_mov_b64_e32 v[86:87], 0
	v_mov_b64_e32 v[88:89], 0
	v_mov_b64_e32 v[90:91], 0
	v_mov_b64_e32 v[92:93], 0
	v_mov_b64_e32 v[94:95], 0
	v_mov_b64_e32 v[96:97], 0
	v_mov_b64_e32 v[98:99], 0
	v_mov_b64_e32 v[100:101], 0
	v_mov_b64_e32 v[102:103], 0
	v_mov_b64_e32 v[104:105], 0
	v_mov_b64_e32 v[106:107], 0
	v_mov_b64_e32 v[108:109], 0
	v_mov_b64_e32 v[110:111], 0
	v_mov_b64_e32 v[112:113], 0
	v_mov_b64_e32 v[114:115], 0
	v_mov_b64_e32 v[116:117], 0
	v_mov_b64_e32 v[118:119], 0
	v_mov_b64_e32 v[120:121], 0
	v_mov_b64_e32 v[122:123], 0
	v_mov_b64_e32 v[124:125], 0
	v_mov_b64_e32 v[126:127], 0
	v_mov_b64_e32 v[128:129], 0
	v_mov_b64_e32 v[130:131], 0
	.p2align	6

;     __device__ __forceinline__ const char* pa(const Gemm& g, const Unit& u, size_t tstep) const { return (const char*)g.A + (size_t)u.pm * tstep; }
;     __device__ __forceinline__ const char* pb(const Gemm& g, const Unit& u, size_t tstep) const { return (const char*)g.Bt + (size_t)u.pn * tstep; }
;     __device__ __forceinline__ const char* pa(const Gemm& g, const Unit& u, size_t tstep) const { return (const char*)g.A + (size_t)(u.pn >> 1) * 512 + (size_t)u.pm * tstep; }
;     __device__ __forceinline__ bool next(int i, Unit& u) const { const int ti = i / 3, sg = i - 3 * ti; if (!StaticOrder::next(ti, u)) return false; u.seg = sg; return true; }
;     __device__ __forceinline__ const char* pa(const Gemm& g, const Unit& u, size_t tstep) const { return (const char*)g.A + (size_t)u.seg * astride + (size_t)u.pm * tstep; }
;     __device__ __forceinline__ const char* pb(const Gemm& g, const Unit& u, size_t tstep) const { return (const char*)g.Bt + (size_t)u.seg * bstride + (size_t)u.pn * tstep; }
;     ...
;     for (int a = 0; a < 2; ++a)
; #pragma unroll
;         for (int b = 0; b < 2; ++b)
; #pragma unroll
;             for (int m = 0; m < 4; ++m)
; #pragma unroll
;                 for (int n = 0; n < 2; ++n) acc[a][b][m][n] = (f32x4){0.f, 0.f, 0.f, 0.f};
;     ...
;     for (;;) {
;         const bool has_next = S.next(ui + 1, nxt);
;         const char* nA = has_next ? S.pa(g, nxt, tstepA) : cA; const char* nB = has_next ? S.pb(g, nxt, tstepB) : cB;
;         for (int t = 0; t < nt; t += 2) {
;             const bool last = (t == nt - 2);
;             const char* a1 = cA + (size_t)(t + 1) * kstep;
;             const char* a2 = last ? nA : cA + (size_t)(t + 2) * kstep; const char* b2 = last ? nB : cB + (size_t)(t + 2) * kstep;
;             const char* a3 = a2 + kstep; const char* b3 = b2 + kstep;
.LBB0_725:
	s_add_u32 s61, s44, 0x100
	v_mov_b32_e32 v36, 0
	s_addc_u32 s62, s45, 0
	s_mov_b32 s63, -2
	v_mov_b32_e32 v37, v36
	v_mov_b32_e32 v38, v36
	v_mov_b32_e32 v39, v36
	v_mov_b32_e32 v40, v36
	v_mov_b32_e32 v41, v36
	v_mov_b32_e32 v42, v36
	v_mov_b32_e32 v43, v36
	v_mov_b32_e32 v44, v36
	v_mov_b32_e32 v45, v36
	v_mov_b32_e32 v46, v36
	v_mov_b32_e32 v47, v36
	v_mov_b32_e32 v52, v36
	v_mov_b32_e32 v53, v36
	v_mov_b32_e32 v54, v36
	v_mov_b32_e32 v55, v36
	v_mov_b32_e32 v60, v36
	v_mov_b32_e32 v61, v36
	v_mov_b32_e32 v62, v36
	v_mov_b32_e32 v63, v36
	v_mov_b32_e32 v68, v36
	v_mov_b32_e32 v69, v36
	v_mov_b32_e32 v70, v36
	v_mov_b32_e32 v71, v36
	v_mov_b32_e32 v76, v36
	v_mov_b32_e32 v77, v36
	v_mov_b32_e32 v78, v36
	v_mov_b32_e32 v79, v36
	v_mov_b32_e32 v84, v36
	v_mov_b32_e32 v85, v36
	v_mov_b32_e32 v86, v36
	v_mov_b32_e32 v87, v36
	v_mov_b32_e32 v48, v36
	v_mov_b32_e32 v49, v36
	v_mov_b32_e32 v50, v36
	v_mov_b32_e32 v51, v36
	v_mov_b32_e32 v56, v36
	v_mov_b32_e32 v57, v36
	v_mov_b32_e32 v58, v36
	v_mov_b32_e32 v59, v36
	v_mov_b32_e32 v64, v36
	v_mov_b32_e32 v65, v36
	v_mov_b32_e32 v66, v36
	v_mov_b32_e32 v67, v36
	v_mov_b32_e32 v72, v36
	v_mov_b32_e32 v73, v36
	v_mov_b32_e32 v74, v36
	v_mov_b32_e32 v75, v36
	v_mov_b32_e32 v80, v36
	v_mov_b32_e32 v81, v36
	v_mov_b32_e32 v82, v36
	v_mov_b32_e32 v83, v36
	v_mov_b32_e32 v88, v36
	v_mov_b32_e32 v89, v36
	v_mov_b32_e32 v90, v36
	v_mov_b32_e32 v91, v36
	v_mov_b32_e32 v92, v36
	v_mov_b32_e32 v93, v36
	v_mov_b32_e32 v94, v36
	v_mov_b32_e32 v95, v36
	v_mov_b32_e32 v96, v36
	v_mov_b32_e32 v97, v36
	v_mov_b32_e32 v98, v36
	v_mov_b32_e32 v99, v36
	v_mov_b32_e32 v100, v36
	v_mov_b32_e32 v101, v36
	v_mov_b32_e32 v102, v36
	v_mov_b32_e32 v103, v36
	v_mov_b32_e32 v104, v36
	v_mov_b32_e32 v105, v36
	v_mov_b32_e32 v106, v36
	v_mov_b32_e32 v107, v36
	v_mov_b32_e32 v108, v36
	v_mov_b32_e32 v109, v36
	v_mov_b32_e32 v110, v36
	v_mov_b32_e32 v111, v36
	v_mov_b32_e32 v116, v36
	v_mov_b32_e32 v117, v36
	v_mov_b32_e32 v118, v36
	v_mov_b32_e32 v119, v36
	v_mov_b32_e32 v124, v36
	v_mov_b32_e32 v125, v36
	v_mov_b32_e32 v126, v36
	v_mov_b32_e32 v127, v36
	v_mov_b32_e32 v132, v36
	v_mov_b32_e32 v133, v36
	v_mov_b32_e32 v134, v36
	v_mov_b32_e32 v135, v36
	v_mov_b32_e32 v140, v36
	v_mov_b32_e32 v141, v36
	v_mov_b32_e32 v142, v36
	v_mov_b32_e32 v143, v36
	v_mov_b32_e32 v148, v36
	v_mov_b32_e32 v149, v36
	v_mov_b32_e32 v150, v36
	v_mov_b32_e32 v151, v36
	v_mov_b32_e32 v112, v36
	v_mov_b32_e32 v113, v36
	v_mov_b32_e32 v114, v36
	v_mov_b32_e32 v115, v36
	v_mov_b32_e32 v120, v36
	v_mov_b32_e32 v121, v36
	v_mov_b32_e32 v122, v36
	v_mov_b32_e32 v123, v36
	v_mov_b32_e32 v128, v36
	v_mov_b32_e32 v129, v36
	v_mov_b32_e32 v130, v36
	v_mov_b32_e32 v131, v36
	v_mov_b32_e32 v136, v36
	v_mov_b32_e32 v137, v36
	v_mov_b32_e32 v138, v36
	v_mov_b32_e32 v139, v36
	v_mov_b32_e32 v144, v36
	v_mov_b32_e32 v145, v36
	v_mov_b32_e32 v146, v36
	v_mov_b32_e32 v147, v36
	v_mov_b32_e32 v152, v36
	v_mov_b32_e32 v153, v36
	v_mov_b32_e32 v154, v36
	v_mov_b32_e32 v155, v36
	v_mov_b32_e32 v156, v36
	v_mov_b32_e32 v157, v36
	v_mov_b32_e32 v158, v36
	v_mov_b32_e32 v159, v36
	v_mov_b32_e32 v160, v36
	v_mov_b32_e32 v161, v36
	v_mov_b32_e32 v162, v36
	v_mov_b32_e32 v163, v36
	.p2align	6

;     __device__ __forceinline__ const char* pa(const Gemm& g, const Unit& u, size_t tstep) const { return (const char*)g.A + (size_t)u.pm * tstep; }
;     __device__ __forceinline__ const char* pb(const Gemm& g, const Unit& u, size_t tstep) const { return (const char*)g.Bt + (size_t)u.pn * tstep; }
;     __device__ __forceinline__ const char* pa(const Gemm& g, const Unit& u, size_t tstep) const { return (const char*)g.A + (size_t)(u.pn >> 1) * 512 + (size_t)u.pm * tstep; }
;     __device__ __forceinline__ bool next(int i, Unit& u) const { const int ti = i / 3, sg = i - 3 * ti; if (!StaticOrder::next(ti, u)) return false; u.seg = sg; return true; }
;     __device__ __forceinline__ const char* pa(const Gemm& g, const Unit& u, size_t tstep) const { return (const char*)g.A + (size_t)u.seg * astride + (size_t)u.pm * tstep; }
;     __device__ __forceinline__ const char* pb(const Gemm& g, const Unit& u, size_t tstep) const { return (const char*)g.Bt + (size_t)u.seg * bstride + (size_t)u.pn * tstep; }
;     ...
;     for (int a = 0; a < 2; ++a)
; #pragma unroll
;         for (int b = 0; b < 2; ++b)
; #pragma unroll
;             for (int m = 0; m < 4; ++m)
; #pragma unroll
;                 for (int n = 0; n < 2; ++n) acc[a][b][m][n] = (f32x4){0.f, 0.f, 0.f, 0.f};
;     ...
;     for (;;) {
;         const bool has_next = S.next(ui + 1, nxt);
;         const char* nA = has_next ? S.pa(g, nxt, tstepA) : cA; const char* nB = has_next ? S.pb(g, nxt, tstepB) : cB;
;         for (int t = 0; t < nt; t += 2) {
;             const bool last = (t == nt - 2);
;             const char* a1 = cA + (size_t)(t + 1) * kstep;
;             const char* a2 = last ? nA : cA + (size_t)(t + 2) * kstep; const char* b2 = last ? nB : cB + (size_t)(t + 2) * kstep;
;             const char* a3 = a2 + kstep; const char* b3 = b2 + kstep;
.LBB0_922:
	s_ashr_i32 s47, s46, 31
	s_lshl_b64 s[34:35], s[46:47], 20
	s_add_u32 s48, s60, s34
	s_addc_u32 s49, s61, s35
	s_and_b64 s[34:35], s[38:39], exec
	s_cselect_b32 s6, s49, s53
	s_cselect_b32 s15, s48, s52
	s_ashr_i32 s37, s36, 31
	s_lshl_b64 s[34:35], s[36:37], 20
	s_add_u32 s50, s62, s34
	s_addc_u32 s51, s63, s35
	s_and_b64 s[34:35], s[38:39], exec
	s_cselect_b32 s34, s51, s57
	s_cselect_b32 s35, s50, s56
	s_add_u32 s52, s52, 0x80080
	s_addc_u32 s53, s53, 0
	s_add_u32 s37, s56, 0x100
	v_mov_b32_e32 v2, 0
	s_addc_u32 s41, s57, 0
	s_mov_b32 s47, -2
	v_mov_b32_e32 v3, v2
	v_mov_b64_e32 v[4:5], 0
	v_mov_b64_e32 v[6:7], 0
	v_mov_b64_e32 v[8:9], 0
	v_mov_b64_e32 v[10:11], 0
	v_mov_b64_e32 v[12:13], 0
	v_mov_b64_e32 v[14:15], 0
	v_mov_b64_e32 v[16:17], 0
	v_mov_b64_e32 v[18:19], 0
	v_mov_b64_e32 v[20:21], 0
	v_mov_b64_e32 v[22:23], 0
	v_mov_b64_e32 v[24:25], 0
	v_mov_b64_e32 v[26:27], 0
	v_mov_b64_e32 v[28:29], 0
	v_mov_b64_e32 v[30:31], 0
	v_mov_b64_e32 v[32:33], 0
	v_mov_b64_e32 v[36:37], 0
	v_mov_b64_e32 v[38:39], 0
	v_mov_b64_e32 v[40:41], 0
	v_mov_b64_e32 v[42:43], 0
	v_mov_b64_e32 v[44:45], 0
	v_mov_b64_e32 v[46:47], 0
	v_mov_b64_e32 v[48:49], 0
	v_mov_b64_e32 v[50:51], 0
	v_mov_b64_e32 v[52:53], 0
	v_mov_b64_e32 v[54:55], 0
	v_mov_b64_e32 v[56:57], 0
	v_mov_b64_e32 v[58:59], 0
	v_mov_b64_e32 v[60:61], 0
	v_mov_b64_e32 v[62:63], 0
	v_mov_b64_e32 v[64:65], 0
	v_mov_b64_e32 v[66:67], 0
	v_mov_b64_e32 v[68:69], 0
	v_mov_b64_e32 v[70:71], 0
	v_mov_b64_e32 v[72:73], 0
	v_mov_b64_e32 v[74:75], 0
	v_mov_b64_e32 v[76:77], 0
	v_mov_b64_e32 v[78:79], 0
	v_mov_b64_e32 v[80:81], 0
	v_mov_b64_e32 v[82:83], 0
	v_mov_b64_e32 v[84:85], 0
	v_mov_b64_e32 v[86:87], 0
	v_mov_b64_e32 v[88:89], 0
	v_mov_b64_e32 v[90:91], 0
	v_mov_b64_e32 v[92:93], 0
	v_mov_b64_e32 v[94:95], 0
	v_mov_b64_e32 v[96:97], 0
	v_mov_b64_e32 v[98:99], 0
	v_mov_b64_e32 v[100:101], 0
	v_mov_b64_e32 v[102:103], 0
	v_mov_b64_e32 v[104:105], 0
	v_mov_b64_e32 v[106:107], 0
	v_mov_b64_e32 v[108:109], 0
	v_mov_b64_e32 v[110:111], 0
	v_mov_b64_e32 v[112:113], 0
	v_mov_b64_e32 v[114:115], 0
	v_mov_b64_e32 v[116:117], 0
	v_mov_b64_e32 v[118:119], 0
	v_mov_b64_e32 v[120:121], 0
	v_mov_b64_e32 v[122:123], 0
	v_mov_b64_e32 v[124:125], 0
	v_mov_b64_e32 v[126:127], 0
	v_mov_b64_e32 v[128:129], 0
	v_mov_b64_e32 v[130:131], 0
	.p2align	6

;     __device__ __forceinline__ const char* pa(const Gemm& g, const Unit& u, size_t tstep) const { return (const char*)g.A + (size_t)u.pm * tstep; }
;     __device__ __forceinline__ const char* pb(const Gemm& g, const Unit& u, size_t tstep) const { return (const char*)g.Bt + (size_t)u.pn * tstep; }
;     __device__ __forceinline__ const char* pa(const Gemm& g, const Unit& u, size_t tstep) const { return (const char*)g.A + (size_t)(u.pn >> 1) * 512 + (size_t)u.pm * tstep; }
;     __device__ __forceinline__ bool next(int i, Unit& u) const { const int ti = i / 3, sg = i - 3 * ti; if (!StaticOrder::next(ti, u)) return false; u.seg = sg; return true; }
;     __device__ __forceinline__ const char* pa(const Gemm& g, const Unit& u, size_t tstep) const { return (const char*)g.A + (size_t)u.seg * astride + (size_t)u.pm * tstep; }
;     __device__ __forceinline__ const char* pb(const Gemm& g, const Unit& u, size_t tstep) const { return (const char*)g.Bt + (size_t)u.seg * bstride + (size_t)u.pn * tstep; }
;     ...
;     for (int a = 0; a < 2; ++a)
; #pragma unroll
;         for (int b = 0; b < 2; ++b)
; #pragma unroll
;             for (int m = 0; m < 4; ++m)
; #pragma unroll
;                 for (int n = 0; n < 2; ++n) acc[a][b][m][n] = (f32x4){0.f, 0.f, 0.f, 0.f};
;     ...
;     for (;;) {
;         const bool has_next = S.next(ui + 1, nxt);
;         const char* nA = has_next ? S.pa(g, nxt, tstepA) : cA; const char* nB = has_next ? S.pb(g, nxt, tstepB) : cB;
;         for (int t = 0; t < nt; t += 2) {
;             const bool last = (t == nt - 2);
;             const char* a1 = cA + (size_t)(t + 1) * kstep;
;             const char* a2 = last ? nA : cA + (size_t)(t + 2) * kstep; const char* b2 = last ? nB : cB + (size_t)(t + 2) * kstep;
;             const char* a3 = a2 + kstep; const char* b3 = b2 + kstep;
.LBB0_1132:
	s_ashr_i32 s37, s36, 31
	s_lshl_b64 s[40:41], s[36:37], 19
	s_add_u32 s40, s12, s40
	s_addc_u32 s41, s13, s41
	s_and_b64 s[46:47], s[38:39], exec
	s_cselect_b32 s37, s41, s51
	s_cselect_b32 s67, s40, s50
	s_ashr_i32 s31, s30, 31
	s_lshl_b64 s[46:47], s[30:31], 19
	s_add_u32 s46, s7, s46
	s_addc_u32 s47, s8, s47
	s_and_b64 s[54:55], s[38:39], exec
	s_cselect_b32 s31, s47, s53
	s_cselect_b32 s68, s46, s52
	s_add_u32 s50, s50, 0x40080
	s_addc_u32 s51, s51, 0
	s_add_u32 s70, s52, 0x100
	v_mov_b32_e32 v36, 0
	s_addc_u32 s71, s53, 0
	s_mov_b32 s74, -2
	v_mov_b32_e32 v37, v36
	v_mov_b32_e32 v38, v36
	v_mov_b32_e32 v39, v36
	v_mov_b32_e32 v40, v36
	v_mov_b32_e32 v41, v36
	v_mov_b32_e32 v42, v36
	v_mov_b32_e32 v43, v36
	v_mov_b32_e32 v52, v36
	v_mov_b32_e32 v53, v36
	v_mov_b32_e32 v54, v36
	v_mov_b32_e32 v55, v36
	v_mov_b32_e32 v56, v36
	v_mov_b32_e32 v57, v36
	v_mov_b32_e32 v58, v36
	v_mov_b32_e32 v59, v36
	v_mov_b32_e32 v68, v36
	v_mov_b32_e32 v69, v36
	v_mov_b32_e32 v70, v36
	v_mov_b32_e32 v71, v36
	v_mov_b32_e32 v72, v36
	v_mov_b32_e32 v73, v36
	v_mov_b32_e32 v74, v36
	v_mov_b32_e32 v75, v36
	v_mov_b32_e32 v84, v36
	v_mov_b32_e32 v85, v36
	v_mov_b32_e32 v86, v36
	v_mov_b32_e32 v87, v36
	v_mov_b32_e32 v88, v36
	v_mov_b32_e32 v89, v36
	v_mov_b32_e32 v90, v36
	v_mov_b32_e32 v91, v36
	v_mov_b32_e32 v44, v36
	v_mov_b32_e32 v45, v36
	v_mov_b32_e32 v46, v36
	v_mov_b32_e32 v47, v36
	v_mov_b32_e32 v48, v36
	v_mov_b32_e32 v49, v36
	v_mov_b32_e32 v50, v36
	v_mov_b32_e32 v51, v36
	v_mov_b32_e32 v60, v36
	v_mov_b32_e32 v61, v36
	v_mov_b32_e32 v62, v36
	v_mov_b32_e32 v63, v36
	v_mov_b32_e32 v64, v36
	v_mov_b32_e32 v65, v36
	v_mov_b32_e32 v66, v36
	v_mov_b32_e32 v67, v36
	v_mov_b32_e32 v76, v36
	v_mov_b32_e32 v77, v36
	v_mov_b32_e32 v78, v36
	v_mov_b32_e32 v79, v36
	v_mov_b32_e32 v80, v36
	v_mov_b32_e32 v81, v36
	v_mov_b32_e32 v82, v36
	v_mov_b32_e32 v83, v36
	v_mov_b32_e32 v92, v36
	v_mov_b32_e32 v93, v36
	v_mov_b32_e32 v94, v36
	v_mov_b32_e32 v95, v36
	v_mov_b32_e32 v96, v36
	v_mov_b32_e32 v97, v36
	v_mov_b32_e32 v98, v36
	v_mov_b32_e32 v99, v36
	v_mov_b32_e32 v100, v36
	v_mov_b32_e32 v101, v36
	v_mov_b32_e32 v102, v36
	v_mov_b32_e32 v103, v36
	v_mov_b32_e32 v104, v36
	v_mov_b32_e32 v105, v36
	v_mov_b32_e32 v106, v36
	v_mov_b32_e32 v107, v36
	v_mov_b32_e32 v116, v36
	v_mov_b32_e32 v117, v36
	v_mov_b32_e32 v118, v36
	v_mov_b32_e32 v119, v36
	v_mov_b32_e32 v120, v36
	v_mov_b32_e32 v121, v36
	v_mov_b32_e32 v122, v36
	v_mov_b32_e32 v123, v36
	v_mov_b32_e32 v132, v36
	v_mov_b32_e32 v133, v36
	v_mov_b32_e32 v134, v36
	v_mov_b32_e32 v135, v36
	v_mov_b32_e32 v136, v36
	v_mov_b32_e32 v137, v36
	v_mov_b32_e32 v138, v36
	v_mov_b32_e32 v139, v36
	v_mov_b32_e32 v148, v36
	v_mov_b32_e32 v149, v36
	v_mov_b32_e32 v150, v36
	v_mov_b32_e32 v151, v36
	v_mov_b32_e32 v152, v36
	v_mov_b32_e32 v153, v36
	v_mov_b32_e32 v154, v36
	v_mov_b32_e32 v155, v36
	v_mov_b32_e32 v108, v36
	v_mov_b32_e32 v109, v36
	v_mov_b32_e32 v110, v36
	v_mov_b32_e32 v111, v36
	v_mov_b32_e32 v112, v36
	v_mov_b32_e32 v113, v36
	v_mov_b32_e32 v114, v36
	v_mov_b32_e32 v115, v36
	v_mov_b32_e32 v124, v36
	v_mov_b32_e32 v125, v36
	v_mov_b32_e32 v126, v36
	v_mov_b32_e32 v127, v36
	v_mov_b32_e32 v128, v36
	v_mov_b32_e32 v129, v36
	v_mov_b32_e32 v130, v36
	v_mov_b32_e32 v131, v36
	v_mov_b32_e32 v140, v36
	v_mov_b32_e32 v141, v36
	v_mov_b32_e32 v142, v36
	v_mov_b32_e32 v143, v36
	v_mov_b32_e32 v144, v36
	v_mov_b32_e32 v145, v36
	v_mov_b32_e32 v146, v36
	v_mov_b32_e32 v147, v36
	v_mov_b32_e32 v156, v36
	v_mov_b32_e32 v157, v36
	v_mov_b32_e32 v158, v36
	v_mov_b32_e32 v159, v36
	v_mov_b32_e32 v160, v36
	v_mov_b32_e32 v161, v36
	v_mov_b32_e32 v162, v36
	v_mov_b32_e32 v163, v36
	.p2align	6

;     __device__ __forceinline__ const char* pa(const Gemm& g, const Unit& u, size_t tstep) const { return (const char*)g.A + (size_t)u.pm * tstep; }
;     __device__ __forceinline__ const char* pb(const Gemm& g, const Unit& u, size_t tstep) const { return (const char*)g.Bt + (size_t)u.pn * tstep; }
;     __device__ __forceinline__ const char* pa(const Gemm& g, const Unit& u, size_t tstep) const { return (const char*)g.A + (size_t)(u.pn >> 1) * 512 + (size_t)u.pm * tstep; }
;     __device__ __forceinline__ bool next(int i, Unit& u) const { const int ti = i / 3, sg = i - 3 * ti; if (!StaticOrder::next(ti, u)) return false; u.seg = sg; return true; }
;     __device__ __forceinline__ const char* pa(const Gemm& g, const Unit& u, size_t tstep) const { return (const char*)g.A + (size_t)u.seg * astride + (size_t)u.pm * tstep; }
;     __device__ __forceinline__ const char* pb(const Gemm& g, const Unit& u, size_t tstep) const { return (const char*)g.Bt + (size_t)u.seg * bstride + (size_t)u.pn * tstep; }
;     ...
;     for (int a = 0; a < 2; ++a)
; #pragma unroll
;         for (int b = 0; b < 2; ++b)
; #pragma unroll
;             for (int m = 0; m < 4; ++m)
; #pragma unroll
;                 for (int n = 0; n < 2; ++n) acc[a][b][m][n] = (f32x4){0.f, 0.f, 0.f, 0.f};
;     ...
;     for (;;) {
;         const bool has_next = S.next(ui + 1, nxt);
;         const char* nA = has_next ? S.pa(g, nxt, tstepA) : cA; const char* nB = has_next ? S.pb(g, nxt, tstepB) : cB;
;         for (int t = 0; t < nt; t += 2) {
;             const bool last = (t == nt - 2);
;             const char* a1 = cA + (size_t)(t + 1) * kstep;
;             const char* a2 = last ? nA : cA + (size_t)(t + 2) * kstep; const char* b2 = last ? nB : cB + (size_t)(t + 2) * kstep;
;             const char* a3 = a2 + kstep; const char* b3 = b2 + kstep;
.LBB0_1152:
	s_ashr_i32 s49, s48, 31
	s_lshl_b64 s[10:11], s[48:49], 20
	s_add_u32 s50, s60, s10
	s_addc_u32 s51, s61, s11
	s_and_b64 s[10:11], s[38:39], exec
	s_cselect_b32 s6, s51, s27
	s_cselect_b32 s10, s50, s26
	s_ashr_i32 s19, s18, 31
	s_lshl_b64 s[12:13], s[18:19], 20
	s_add_u32 s52, s62, s12
	s_addc_u32 s53, s63, s13
	s_and_b64 s[12:13], s[38:39], exec
	s_cselect_b32 s11, s53, s41
	s_cselect_b32 s12, s52, s40
	s_add_u32 s26, s26, 0x80080
	s_addc_u32 s27, s27, 0
	s_add_u32 s13, s40, 0x100
	v_mov_b32_e32 v2, 0
	s_addc_u32 s15, s41, 0
	s_mov_b32 s19, -2
	v_mov_b32_e32 v3, v2
	v_mov_b64_e32 v[4:5], 0
	v_mov_b64_e32 v[6:7], 0
	v_mov_b64_e32 v[8:9], 0
	v_mov_b64_e32 v[10:11], 0
	v_mov_b64_e32 v[12:13], 0
	v_mov_b64_e32 v[14:15], 0
	v_mov_b64_e32 v[16:17], 0
	v_mov_b64_e32 v[18:19], 0
	v_mov_b64_e32 v[20:21], 0
	v_mov_b64_e32 v[22:23], 0
	v_mov_b64_e32 v[24:25], 0
	v_mov_b64_e32 v[26:27], 0
	v_mov_b64_e32 v[28:29], 0
	v_mov_b64_e32 v[30:31], 0
	v_mov_b64_e32 v[32:33], 0
	v_mov_b64_e32 v[36:37], 0
	v_mov_b64_e32 v[38:39], 0
	v_mov_b64_e32 v[40:41], 0
	v_mov_b64_e32 v[42:43], 0
	v_mov_b64_e32 v[44:45], 0
	v_mov_b64_e32 v[46:47], 0
	v_mov_b64_e32 v[48:49], 0
	v_mov_b64_e32 v[50:51], 0
	v_mov_b64_e32 v[52:53], 0
	v_mov_b64_e32 v[54:55], 0
	v_mov_b64_e32 v[56:57], 0
	v_mov_b64_e32 v[58:59], 0
	v_mov_b64_e32 v[60:61], 0
	v_mov_b64_e32 v[62:63], 0
	v_mov_b64_e32 v[64:65], 0
	v_mov_b64_e32 v[66:67], 0
	v_mov_b64_e32 v[68:69], 0
	v_mov_b64_e32 v[70:71], 0
	v_mov_b64_e32 v[72:73], 0
	v_mov_b64_e32 v[74:75], 0
	v_mov_b64_e32 v[76:77], 0
	v_mov_b64_e32 v[78:79], 0
	v_mov_b64_e32 v[80:81], 0
	v_mov_b64_e32 v[82:83], 0
	v_mov_b64_e32 v[84:85], 0
	v_mov_b64_e32 v[86:87], 0
	v_mov_b64_e32 v[88:89], 0
	v_mov_b64_e32 v[90:91], 0
	v_mov_b64_e32 v[92:93], 0
	v_mov_b64_e32 v[94:95], 0
	v_mov_b64_e32 v[96:97], 0
	v_mov_b64_e32 v[98:99], 0
	v_mov_b64_e32 v[100:101], 0
	v_mov_b64_e32 v[102:103], 0
	v_mov_b64_e32 v[104:105], 0
	v_mov_b64_e32 v[106:107], 0
	v_mov_b64_e32 v[108:109], 0
	v_mov_b64_e32 v[110:111], 0
	v_mov_b64_e32 v[112:113], 0
	v_mov_b64_e32 v[114:115], 0
	v_mov_b64_e32 v[116:117], 0
	v_mov_b64_e32 v[118:119], 0
	v_mov_b64_e32 v[120:121], 0
	v_mov_b64_e32 v[122:123], 0
	v_mov_b64_e32 v[124:125], 0
	v_mov_b64_e32 v[126:127], 0
	v_mov_b64_e32 v[128:129], 0
	v_mov_b64_e32 v[130:131], 0
	.p2align	6

;     __device__ __forceinline__ const char* pa(const Gemm& g, const Unit& u, size_t tstep) const { return (const char*)g.A + (size_t)u.pm * tstep; }
;     __device__ __forceinline__ const char* pb(const Gemm& g, const Unit& u, size_t tstep) const { return (const char*)g.Bt + (size_t)u.pn * tstep; }
; #define PG8_WAIT_V(n) asm volatile("s_waitcnt vmcnt(" #n ")" ::: "memory")
; #define PG8_BAR __builtin_amdgcn_s_barrier()
;     __device__ __forceinline__ const char* pa(const Gemm& g, const Unit& u, size_t tstep) const { return (const char*)g.A + (size_t)(u.pn >> 1) * 512 + (size_t)u.pm * tstep; }
;     ...
;     for (int a = 0; a < 2; ++a)
; #pragma unroll
;         for (int b = 0; b < 2; ++b)
; #pragma unroll
;             for (int m = 0; m < 4; ++m)
; #pragma unroll
;                 for (int n = 0; n < 2; ++n) acc[a][b][m][n] = (f32x4){0.f, 0.f, 0.f, 0.f};
;     bf16x8 At[4][2], B0[2][2], B1[2][2];
;     const char* cA = S.pa(g, cur, tstepA); const char* cB = S.pb(g, cur, tstepB);
;     S.a_ready(cur);
;     if constexpr (SP2) {
;         PG8_STAGE(PG8_SB(0, 0), cB, voffB); PG8_STAGE(PG8_SB(0, 1), cB + hstepB, voffB); PG8_STAGE(PG8_SA(0, 0), cA, voffA); PG8_STAGE(PG8_SA(0, 1), cA + hstepA, voffA);
;         if (wr == 1) PG8_BAR;
;         PG8_WAIT_V(2); PG8_BAR;
;         PG8_STAGE(PG8_SB(1, 0), cB + kstep, voffB); PG8_STAGE(PG8_SA(1, 0), cA + kstep, voffA); PG8_STAGE(PG8_SB(1, 1), cB + hstepB + kstep, voffB);
;         PG8_WAIT_V(6); PG8_BAR;
;     } else {
;         PG8_STAGE(PG8_SB(0, 0), cB, voffB); PG8_STAGE(PG8_SA(0, 0), cA, voffA); PG8_STAGE(PG8_SB(0, 1), cB + hstepB, voffB); PG8_STAGE(PG8_SA(0, 1), cA + hstepA, voffA);
;         if (wr == 1) PG8_BAR;
;         PG8_WAIT_V(4); PG8_BAR;
;         PG8_STAGE(PG8_SB(1, 0), cB + kstep, voffB); PG8_STAGE(PG8_SA(1, 0), cA + kstep, voffA); PG8_STAGE(PG8_SB(1, 1), cB + hstepB + kstep, voffB);
;         PG8_WAIT_V(6); PG8_BAR;
;     }
;     for (;;) {
;         const bool has_next = S.next(ui + 1, nxt);
;         const char* nA = has_next ? S.pa(g, nxt, tstepA) : cA; const char* nB = has_next ? S.pb(g, nxt, tstepB) : cB;
;         for (int t = 0; t < nt; t += 2) {
;             const bool last = (t == nt - 2);
;             const char* a1 = cA + (size_t)(t + 1) * kstep;
;             const char* a2 = last ? nA : cA + (size_t)(t + 2) * kstep; const char* b2 = last ? nB : cB + (size_t)(t + 2) * kstep;
.LBB0_1501:
	s_ashr_i32 s54, s66, 1
	s_ashr_i32 s55, s54, 31
	s_lshl_b64 s[54:55], s[54:55], 9
	s_add_u32 s68, s18, s54
	s_addc_u32 s70, s19, s55
	s_ashr_i32 s51, s50, 31
	s_lshl_b64 s[54:55], s[50:51], 19
	s_add_u32 s54, s68, s54
	v_mov_b32_e32 v147, 0
	s_addc_u32 s55, s70, s55
	s_andn2_b64 vcc, exec, s[46:47]
	v_mov_b32_e32 v146, v147
	v_mov_b32_e32 v145, v147
	v_mov_b32_e32 v144, v147
	v_mov_b32_e32 v143, v147
	v_mov_b32_e32 v142, v147
	v_mov_b32_e32 v141, v147
	v_mov_b32_e32 v140, v147
	v_mov_b32_e32 v123, v147
	v_mov_b32_e32 v122, v147
	v_mov_b32_e32 v121, v147
	v_mov_b32_e32 v120, v147
	v_mov_b32_e32 v119, v147
	v_mov_b32_e32 v118, v147
	v_mov_b32_e32 v117, v147
	v_mov_b32_e32 v116, v147
	v_mov_b32_e32 v99, v147
	v_mov_b32_e32 v98, v147
	v_mov_b32_e32 v97, v147
	v_mov_b32_e32 v96, v147
	v_mov_b32_e32 v95, v147
	v_mov_b32_e32 v94, v147
	v_mov_b32_e32 v93, v147
	v_mov_b32_e32 v92, v147
	v_mov_b32_e32 v83, v147
	v_mov_b32_e32 v82, v147
	v_mov_b32_e32 v81, v147
	v_mov_b32_e32 v80, v147
	v_mov_b32_e32 v79, v147
	v_mov_b32_e32 v78, v147
	v_mov_b32_e32 v77, v147
	v_mov_b32_e32 v76, v147
	v_mov_b32_e32 v139, v147
	v_mov_b32_e32 v138, v147
	v_mov_b32_e32 v137, v147
	v_mov_b32_e32 v136, v147
	v_mov_b32_e32 v135, v147
	v_mov_b32_e32 v134, v147
	v_mov_b32_e32 v133, v147
	v_mov_b32_e32 v132, v147
	v_mov_b32_e32 v107, v147
	v_mov_b32_e32 v106, v147
	v_mov_b32_e32 v105, v147
	v_mov_b32_e32 v104, v147
	v_mov_b32_e32 v103, v147
	v_mov_b32_e32 v102, v147
	v_mov_b32_e32 v101, v147
	v_mov_b32_e32 v100, v147
	v_mov_b32_e32 v91, v147
	v_mov_b32_e32 v90, v147
	v_mov_b32_e32 v89, v147
	v_mov_b32_e32 v88, v147
	v_mov_b32_e32 v87, v147
	v_mov_b32_e32 v86, v147
	v_mov_b32_e32 v85, v147
	v_mov_b32_e32 v84, v147
	v_mov_b32_e32 v75, v147
	v_mov_b32_e32 v74, v147
	v_mov_b32_e32 v73, v147
	v_mov_b32_e32 v72, v147
	v_mov_b32_e32 v71, v147
	v_mov_b32_e32 v70, v147
	v_mov_b32_e32 v69, v147
	v_mov_b32_e32 v68, v147
	v_mov_b32_e32 v67, v147
	v_mov_b32_e32 v66, v147
	v_mov_b32_e32 v65, v147
	v_mov_b32_e32 v64, v147
	v_mov_b32_e32 v63, v147
	v_mov_b32_e32 v62, v147
	v_mov_b32_e32 v61, v147
	v_mov_b32_e32 v60, v147
	v_mov_b32_e32 v51, v147
	v_mov_b32_e32 v50, v147
	v_mov_b32_e32 v49, v147
	v_mov_b32_e32 v48, v147
	v_mov_b32_e32 v47, v147
	v_mov_b32_e32 v46, v147
	v_mov_b32_e32 v45, v147
	v_mov_b32_e32 v44, v147
	v_mov_b32_e32 v33, v147
	v_mov_b32_e32 v32, v147
	v_mov_b32_e32 v31, v147
	v_mov_b32_e32 v30, v147
	v_mov_b32_e32 v29, v147
	v_mov_b32_e32 v28, v147
	v_mov_b32_e32 v27, v147
	v_mov_b32_e32 v26, v147
	v_mov_b32_e32 v17, v147
	v_mov_b32_e32 v16, v147
	v_mov_b32_e32 v15, v147
	v_mov_b32_e32 v14, v147
	v_mov_b32_e32 v13, v147
	v_mov_b32_e32 v12, v147
	v_mov_b32_e32 v11, v147
	v_mov_b32_e32 v10, v147
	v_mov_b32_e32 v59, v147
	v_mov_b32_e32 v58, v147
	v_mov_b32_e32 v57, v147
	v_mov_b32_e32 v56, v147
	v_mov_b32_e32 v55, v147
	v_mov_b32_e32 v54, v147
	v_mov_b32_e32 v53, v147
	v_mov_b32_e32 v52, v147
	v_mov_b32_e32 v43, v147
	v_mov_b32_e32 v42, v147
	v_mov_b32_e32 v41, v147
	v_mov_b32_e32 v40, v147
	v_mov_b32_e32 v39, v147
	v_mov_b32_e32 v38, v147
	v_mov_b32_e32 v37, v147
	v_mov_b32_e32 v36, v147
	v_mov_b32_e32 v25, v147
	v_mov_b32_e32 v24, v147
	v_mov_b32_e32 v23, v147
	v_mov_b32_e32 v22, v147
	v_mov_b32_e32 v21, v147
	v_mov_b32_e32 v20, v147
	v_mov_b32_e32 v19, v147
	v_mov_b32_e32 v18, v147
	v_mov_b32_e32 v9, v147
	v_mov_b32_e32 v8, v147
	v_mov_b32_e32 v7, v147
	v_mov_b32_e32 v6, v147
	v_mov_b32_e32 v5, v147
	v_mov_b32_e32 v4, v147
	v_mov_b32_e32 v3, v147
	v_mov_b32_e32 v2, v147
	s_cbranch_vccnz .LBB0_1505
	s_and_b64 s[40:41], s[40:41], exec
	s_cselect_b32 s51, s55, s61
	s_cselect_b32 s68, s54, s60
	s_add_u32 s40, s60, 0x40080
	s_addc_u32 s41, s61, 0
	s_add_u32 s60, s58, 0x100
	v_mov_b32_e32 v2, 0
	s_addc_u32 s61, s59, 0
	s_mov_b32 s58, 0
	v_mov_b32_e32 v3, v2
	v_mov_b64_e32 v[4:5], 0
	v_mov_b64_e32 v[6:7], 0
	v_mov_b64_e32 v[8:9], 0
	v_mov_b64_e32 v[10:11], 0
	v_mov_b64_e32 v[12:13], 0
	v_mov_b64_e32 v[14:15], 0
	v_mov_b64_e32 v[16:17], 0
	v_mov_b64_e32 v[18:19], 0
	v_mov_b64_e32 v[20:21], 0
	v_mov_b64_e32 v[22:23], 0
	v_mov_b64_e32 v[24:25], 0
	v_mov_b64_e32 v[26:27], 0
	v_mov_b64_e32 v[28:29], 0
	v_mov_b64_e32 v[30:31], 0
	v_mov_b64_e32 v[32:33], 0
	v_mov_b64_e32 v[36:37], 0
	v_mov_b64_e32 v[38:39], 0
	v_mov_b64_e32 v[40:41], 0
	v_mov_b64_e32 v[42:43], 0
	v_mov_b64_e32 v[44:45], 0
	v_mov_b64_e32 v[46:47], 0
	v_mov_b64_e32 v[48:49], 0
	v_mov_b64_e32 v[50:51], 0
	v_mov_b64_e32 v[52:53], 0
	v_mov_b64_e32 v[54:55], 0
	v_mov_b64_e32 v[56:57], 0
	v_mov_b64_e32 v[58:59], 0
	v_mov_b64_e32 v[60:61], 0
	v_mov_b64_e32 v[62:63], 0
	v_mov_b64_e32 v[64:65], 0
	v_mov_b64_e32 v[66:67], 0
	v_mov_b64_e32 v[68:69], 0
	v_mov_b64_e32 v[70:71], 0
	v_mov_b64_e32 v[72:73], 0
	v_mov_b64_e32 v[74:75], 0
	v_mov_b64_e32 v[76:77], 0
	v_mov_b64_e32 v[78:79], 0
	v_mov_b64_e32 v[80:81], 0
	v_mov_b64_e32 v[82:83], 0
	v_mov_b64_e32 v[84:85], 0
	v_mov_b64_e32 v[86:87], 0
	v_mov_b64_e32 v[88:89], 0
	v_mov_b64_e32 v[90:91], 0
	v_mov_b64_e32 v[92:93], 0
	v_mov_b64_e32 v[94:95], 0
	v_mov_b64_e32 v[96:97], 0
	v_mov_b64_e32 v[98:99], 0
	v_mov_b64_e32 v[100:101], 0
	v_mov_b64_e32 v[102:103], 0
	v_mov_b64_e32 v[104:105], 0
	v_mov_b64_e32 v[106:107], 0
	v_mov_b64_e32 v[116:117], 0
	v_mov_b64_e32 v[118:119], 0
	v_mov_b64_e32 v[120:121], 0
	v_mov_b64_e32 v[122:123], 0
	v_mov_b64_e32 v[132:133], 0
	v_mov_b64_e32 v[134:135], 0
	v_mov_b64_e32 v[136:137], 0
	v_mov_b64_e32 v[138:139], 0
	v_mov_b64_e32 v[140:141], 0
	v_mov_b64_e32 v[142:143], 0
	v_mov_b64_e32 v[144:145], 0
	v_mov_b64_e32 v[146:147], 0
	.p2align	6

;     __device__ __forceinline__ const char* pa(const Gemm& g, const Unit& u, size_t tstep) const { return (const char*)g.A + (size_t)u.pm * tstep; }
;     __device__ __forceinline__ const char* pb(const Gemm& g, const Unit& u, size_t tstep) const { return (const char*)g.Bt + (size_t)u.pn * tstep; }
;     __device__ __forceinline__ const char* pa(const Gemm& g, const Unit& u, size_t tstep) const { return (const char*)g.A + (size_t)(u.pn >> 1) * 512 + (size_t)u.pm * tstep; }
;     __device__ __forceinline__ bool next(int i, Unit& u) const { const int ti = i / 3, sg = i - 3 * ti; if (!StaticOrder::next(ti, u)) return false; u.seg = sg; return true; }
;     __device__ __forceinline__ const char* pa(const Gemm& g, const Unit& u, size_t tstep) const { return (const char*)g.A + (size_t)u.seg * astride + (size_t)u.pm * tstep; }
;     __device__ __forceinline__ const char* pb(const Gemm& g, const Unit& u, size_t tstep) const { return (const char*)g.Bt + (size_t)u.seg * bstride + (size_t)u.pn * tstep; }
;     ...
;     for (;;) {
;         const bool has_next = S.next(ui + 1, nxt);
;         const char* nA = has_next ? S.pa(g, nxt, tstepA) : cA; const char* nB = has_next ? S.pb(g, nxt, tstepB) : cB;
;         for (int t = 0; t < nt; t += 2) {
;             const bool last = (t == nt - 2);
;             const char* a1 = cA + (size_t)(t + 1) * kstep;
;             const char* a2 = last ? nA : cA + (size_t)(t + 2) * kstep; const char* b2 = last ? nB : cB + (size_t)(t + 2) * kstep;
.LBB0_2022:
	s_add_u32 s40, s54, 0x40080
	s_addc_u32 s41, s55, 0
	s_add_u32 s15, s56, 0x100
	s_addc_u32 s24, s57, 0
	s_mov_b32 s34, -2
	.p2align	6

;     __device__ __forceinline__ const char* pa(const Gemm& g, const Unit& u, size_t tstep) const { return (const char*)g.A + (size_t)u.pm * tstep; }
;     __device__ __forceinline__ const char* pb(const Gemm& g, const Unit& u, size_t tstep) const { return (const char*)g.Bt + (size_t)u.pn * tstep; }
;     __device__ __forceinline__ const char* pa(const Gemm& g, const Unit& u, size_t tstep) const { return (const char*)g.A + (size_t)(u.pn >> 1) * 512 + (size_t)u.pm * tstep; }
;     __device__ __forceinline__ bool next(int i, Unit& u) const { const int ti = i / 3, sg = i - 3 * ti; if (!StaticOrder::next(ti, u)) return false; u.seg = sg; return true; }
;     __device__ __forceinline__ const char* pa(const Gemm& g, const Unit& u, size_t tstep) const { return (const char*)g.A + (size_t)u.seg * astride + (size_t)u.pm * tstep; }
;     __device__ __forceinline__ const char* pb(const Gemm& g, const Unit& u, size_t tstep) const { return (const char*)g.Bt + (size_t)u.seg * bstride + (size_t)u.pn * tstep; }
;     ...
;     for (int a = 0; a < 2; ++a)
; #pragma unroll
;         for (int b = 0; b < 2; ++b)
; #pragma unroll
;             for (int m = 0; m < 4; ++m)
; #pragma unroll
;                 for (int n = 0; n < 2; ++n) acc[a][b][m][n] = (f32x4){0.f, 0.f, 0.f, 0.f};
;     ...
;     for (;;) {
;         const bool has_next = S.next(ui + 1, nxt);
;         const char* nA = has_next ? S.pa(g, nxt, tstepA) : cA; const char* nB = has_next ? S.pb(g, nxt, tstepB) : cB;
;         for (int t = 0; t < nt; t += 2) {
;             const bool last = (t == nt - 2);
;             const char* a1 = cA + (size_t)(t + 1) * kstep;
;             const char* a2 = last ? nA : cA + (size_t)(t + 2) * kstep; const char* b2 = last ? nB : cB + (size_t)(t + 2) * kstep;
;             const char* a3 = a2 + kstep; const char* b3 = b2 + kstep;
.LBB0_2137:
	s_ashr_i32 s41, s40, 31
	s_lshl_b64 s[42:43], s[40:41], 20
	s_add_u32 s42, s10, s42
	s_addc_u32 s43, s11, s43
	s_and_b64 s[44:45], s[38:39], exec
	s_cselect_b32 s41, s43, s47
	s_cselect_b32 s56, s42, s46
	s_ashr_i32 s37, s36, 31
	s_lshl_b64 s[44:45], s[36:37], 20
	s_add_u32 s44, s12, s44
	s_addc_u32 s45, s13, s45
	s_and_b64 s[50:51], s[38:39], exec
	s_cselect_b32 s37, s45, s49
	s_cselect_b32 s57, s44, s48
	s_add_u32 s46, s46, 0x80080
	s_addc_u32 s47, s47, 0
	s_add_u32 s58, s48, 0x100
	v_mov_b32_e32 v2, 0
	s_addc_u32 s59, s49, 0
	s_mov_b32 s60, -2
	v_mov_b32_e32 v3, v2
	v_mov_b64_e32 v[4:5], 0
	v_mov_b64_e32 v[6:7], 0
	v_mov_b64_e32 v[8:9], 0
	v_mov_b64_e32 v[10:11], 0
	v_mov_b64_e32 v[12:13], 0
	v_mov_b64_e32 v[14:15], 0
	v_mov_b64_e32 v[16:17], 0
	v_mov_b64_e32 v[18:19], 0
	v_mov_b64_e32 v[20:21], 0
	v_mov_b64_e32 v[22:23], 0
	v_mov_b64_e32 v[24:25], 0
	v_mov_b64_e32 v[26:27], 0
	v_mov_b64_e32 v[28:29], 0
	v_mov_b64_e32 v[30:31], 0
	v_mov_b64_e32 v[32:33], 0
	v_mov_b64_e32 v[36:37], 0
	v_mov_b64_e32 v[38:39], 0
	v_mov_b64_e32 v[40:41], 0
	v_mov_b64_e32 v[42:43], 0
	v_mov_b64_e32 v[44:45], 0
	v_mov_b64_e32 v[46:47], 0
	v_mov_b64_e32 v[48:49], 0
	v_mov_b64_e32 v[50:51], 0
	v_mov_b64_e32 v[52:53], 0
	v_mov_b64_e32 v[54:55], 0
	v_mov_b64_e32 v[56:57], 0
	v_mov_b64_e32 v[58:59], 0
	v_mov_b64_e32 v[60:61], 0
	v_mov_b64_e32 v[62:63], 0
	v_mov_b64_e32 v[64:65], 0
	v_mov_b64_e32 v[66:67], 0
	v_mov_b64_e32 v[68:69], 0
	v_mov_b64_e32 v[70:71], 0
	v_mov_b64_e32 v[72:73], 0
	v_mov_b64_e32 v[74:75], 0
	v_mov_b64_e32 v[76:77], 0
	v_mov_b64_e32 v[78:79], 0
	v_mov_b64_e32 v[80:81], 0
	v_mov_b64_e32 v[82:83], 0
	v_mov_b64_e32 v[84:85], 0
	v_mov_b64_e32 v[86:87], 0
	v_mov_b64_e32 v[88:89], 0
	v_mov_b64_e32 v[90:91], 0
	v_mov_b64_e32 v[92:93], 0
	v_mov_b64_e32 v[94:95], 0
	v_mov_b64_e32 v[96:97], 0
	v_mov_b64_e32 v[98:99], 0
	v_mov_b64_e32 v[100:101], 0
	v_mov_b64_e32 v[102:103], 0
	v_mov_b64_e32 v[104:105], 0
	v_mov_b64_e32 v[106:107], 0
	v_mov_b64_e32 v[108:109], 0
	v_mov_b64_e32 v[110:111], 0
	v_mov_b64_e32 v[112:113], 0
	v_mov_b64_e32 v[114:115], 0
	v_mov_b64_e32 v[116:117], 0
	v_mov_b64_e32 v[118:119], 0
	v_mov_b64_e32 v[120:121], 0
	v_mov_b64_e32 v[122:123], 0
	v_mov_b64_e32 v[124:125], 0
	v_mov_b64_e32 v[126:127], 0
	v_mov_b64_e32 v[128:129], 0
	v_mov_b64_e32 v[130:131], 0
	.p2align	6
